# B-attention epilogue: the 32 exchange reads pipelined 12 deep into dead registers with counted lgkmcnt (were 32 serialized LDS round trips); gain loads moved behind the combine
# speedup vs baseline: 1.0318x; 1.0054x over previous
; template <int DV, int NMAP> ...
;     ...
;         asm volatile("s_waitcnt lgkmcnt(0)" ::: "memory"); __builtin_amdgcn_s_barrier(); asm volatile("" ::: "memory");
;         if (mp == 0) {
;             float ss[2] = {0.f, 0.f};
; #pragma unroll
;             for (int db = 0; db < DV / 16; ++db)
; #pragma unroll
;                 for (int qb = 0; qb < 2; ++qb) { const f32x4 x = o[db][qb] * inv[qb] - xch[(db * 2 + qb) * 64 + lane]; o[db][qb] = x; ss[qb] += (x[0] * x[0] + x[1] * x[1]) + (x[2] * x[2] + x[3] * x[3]); if (qb == 1 && (db & 1)) asm volatile("" ::: "memory"); }
; #pragma unroll
;             for (int qb = 0; qb < 2; ++qb) { float v = ss[qb]; v += __shfl_xor(v, 16); v += __shfl_xor(v, 32); ss[qb] = outscale / sqrtf(v * (1.0f / DV) + RMS_EPS); }
; #pragma unroll
;             for (int db = 0; db < DV / 16; ++db) { const f32x4 g = *(const f32x4*)(subg + 16 * db + 4 * fq);
.LBB0_329:
	s_waitcnt lgkmcnt(0)
	s_barrier
	s_cmpk_gt_u32 s20, 0xff
	v_mov_b64_e32 v[238:239], v[214:215]
	s_cbranch_scc1 .LBB0_297
	ds_read_b128 v[160:163], v129
	ds_read_b128 v[164:167], v129 offset:1024
	ds_read_b128 v[168:171], v129 offset:2048
	ds_read_b128 v[172:175], v129 offset:3072
	ds_read_b128 v[176:179], v129 offset:4096
	ds_read_b128 v[180:183], v129 offset:5120
	ds_read_b128 v[184:187], v129 offset:6144
	ds_read_b128 v[188:191], v129 offset:7168
	ds_read_b128 v[192:195], v129 offset:8192
	ds_read_b128 v[196:199], v129 offset:9216
	ds_read_b128 v[200:203], v129 offset:10240
	ds_read_b128 v[148:151], v129 offset:11264
	v_lshlrev_b32_e32 v204, 3, v236
	s_waitcnt lgkmcnt(11)
	v_xor_b32_e32 v125, 0x80000000, v163
	v_xor_b32_e32 v124, 0x80000000, v162
	v_pk_fma_f32 v[124:125], v[158:159], v[130:131], v[124:125] op_sel_hi:[1,0,1]
	v_pk_fma_f32 v[126:127], v[156:157], v[130:131], v[160:161] op_sel_hi:[1, 0, 1] neg_lo:[0, 0, 1] neg_hi:[0, 0, 1]
	ds_read_b128 v[160:163], v129 offset:12288
	v_pk_mul_f32 v[132:133], v[124:125], v[124:125]
	v_pk_mul_f32 v[134:135], v[126:127], v[126:127]
	s_nop 0
	v_pk_mov_b32 v[136:137], v[134:135], v[132:133] op_sel:[1,0]
	v_mov_b32_e32 v135, v133
	v_pk_add_f32 v[132:133], v[136:137], v[134:135]
	v_pk_add_f32 v[132:133], v[132:133], v[132:133] op_sel:[0,1] op_sel_hi:[1,0]
	s_waitcnt lgkmcnt(11)
	v_xor_b32_e32 v137, 0x80000000, v167
	v_xor_b32_e32 v136, 0x80000000, v166
	v_pk_fma_f32 v[122:123], v[122:123], v[128:129], v[136:137] op_sel_hi:[1,0,1]
	v_pk_fma_f32 v[120:121], v[120:121], v[128:129], v[164:165] op_sel_hi:[1, 0, 1] neg_lo:[0, 0, 1] neg_hi:[0, 0, 1]
	ds_read_b128 v[164:167], v129 offset:13312
	v_pk_mul_f32 v[134:135], v[122:123], v[122:123]
	v_pk_mul_f32 v[136:137], v[120:121], v[120:121]
	s_nop 0
	v_pk_mov_b32 v[138:139], v[136:137], v[134:135] op_sel:[1,0]
	v_mov_b32_e32 v137, v135
	v_pk_add_f32 v[134:135], v[138:139], v[136:137]
	v_pk_add_f32 v[134:135], v[134:135], v[134:135] op_sel:[0,1] op_sel_hi:[1,0]
	s_waitcnt lgkmcnt(11)
	v_xor_b32_e32 v139, 0x80000000, v171
	v_xor_b32_e32 v138, 0x80000000, v170
	v_pk_fma_f32 v[118:119], v[118:119], v[130:131], v[138:139] op_sel_hi:[1,0,1]
	v_pk_fma_f32 v[116:117], v[116:117], v[130:131], v[168:169] op_sel_hi:[1, 0, 1] neg_lo:[0, 0, 1] neg_hi:[0, 0, 1]
	ds_read_b128 v[168:171], v129 offset:14336
	v_pk_mul_f32 v[136:137], v[118:119], v[118:119]
	v_pk_mul_f32 v[138:139], v[116:117], v[116:117]
	s_nop 0
	v_pk_mov_b32 v[140:141], v[138:139], v[136:137] op_sel:[1,0]
	v_mov_b32_e32 v139, v137
	v_pk_add_f32 v[142:143], v[140:141], v[138:139]
	s_waitcnt lgkmcnt(11)
	v_xor_b32_e32 v139, 0x80000000, v175
	v_xor_b32_e32 v138, 0x80000000, v174
	v_pk_fma_f32 v[114:115], v[114:115], v[128:129], v[138:139] op_sel_hi:[1,0,1]
	v_pk_fma_f32 v[112:113], v[112:113], v[128:129], v[172:173] op_sel_hi:[1, 0, 1] neg_lo:[0, 0, 1] neg_hi:[0, 0, 1]
	ds_read_b128 v[172:175], v129 offset:15360
	v_pk_mul_f32 v[136:137], v[114:115], v[114:115]
	v_pk_mul_f32 v[138:139], v[112:113], v[112:113]
	s_nop 0
	v_pk_mov_b32 v[140:141], v[138:139], v[136:137] op_sel:[1,0]
	v_mov_b32_e32 v139, v137
	v_pk_add_f32 v[136:137], v[140:141], v[138:139]
	v_pk_add_f32 v[136:137], v[136:137], v[136:137] op_sel:[0,1] op_sel_hi:[1,0]
	s_waitcnt lgkmcnt(11)
	v_xor_b32_e32 v141, 0x80000000, v179
	v_xor_b32_e32 v140, 0x80000000, v178
	v_pk_fma_f32 v[110:111], v[110:111], v[130:131], v[140:141] op_sel_hi:[1,0,1]
	v_pk_fma_f32 v[108:109], v[108:109], v[130:131], v[176:177] op_sel_hi:[1, 0, 1] neg_lo:[0, 0, 1] neg_hi:[0, 0, 1]
	ds_read_b128 v[176:179], v129 offset:16384
	s_waitcnt lgkmcnt(11)
	v_xor_b32_e32 v141, 0x80000000, v183
	v_xor_b32_e32 v140, 0x80000000, v182
	v_pk_fma_f32 v[106:107], v[106:107], v[128:129], v[140:141] op_sel_hi:[1,0,1]
	v_pk_fma_f32 v[104:105], v[104:105], v[128:129], v[180:181] op_sel_hi:[1, 0, 1] neg_lo:[0, 0, 1] neg_hi:[0, 0, 1]
	ds_read_b128 v[180:183], v129 offset:17408
	s_waitcnt lgkmcnt(11)
	v_xor_b32_e32 v141, 0x80000000, v187
	v_xor_b32_e32 v140, 0x80000000, v186
	v_pk_fma_f32 v[100:101], v[100:101], v[130:131], v[184:185] op_sel_hi:[1, 0, 1] neg_lo:[0, 0, 1] neg_hi:[0, 0, 1]
	ds_read_b128 v[184:187], v129 offset:18432
	v_pk_fma_f32 v[102:103], v[102:103], v[130:131], v[140:141] op_sel_hi:[1,0,1]
	v_mul_f32_e32 v131, v100, v100
	v_mul_f32_e32 v140, v101, v101
	v_pk_add_f32 v[138:139], v[142:143], v[142:143] op_sel:[0,1] op_sel_hi:[1,0]
	v_mov_b32_e32 v133, v131
	v_mov_b32_e32 v139, v140
	v_pk_add_f32 v[132:133], v[132:133], v[138:139]
	v_mul_f32_e32 v138, v109, v109
	v_mul_f32_e32 v141, v102, v102
	v_pk_fma_f32 v[138:139], v[108:109], v[108:109], v[138:139] op_sel_hi:[1,1,0]
	v_mul_f32_e32 v140, v111, v111
	v_mul_f32_e32 v144, v103, v103
	v_mov_b32_e32 v139, v141
	v_pk_fma_f32 v[140:141], v[110:111], v[110:111], v[140:141] op_sel_hi:[1,1,0]
	s_nop 0
	v_mov_b32_e32 v141, v144
	v_pk_add_f32 v[138:139], v[138:139], v[140:141]
	s_nop 0
	v_pk_add_f32 v[132:133], v[132:133], v[138:139]
	v_pk_add_f32 v[132:133], v[132:133], v[132:133] op_sel:[0,1] op_sel_hi:[1,0]
	s_waitcnt lgkmcnt(11)
	v_pk_fma_f32 v[96:97], v[96:97], v[128:129], v[188:189] op_sel_hi:[1, 0, 1] neg_lo:[0, 0, 1] neg_hi:[0, 0, 1]
	s_nop 0
	v_mul_f32_e32 v131, v96, v96
	v_mul_f32_e32 v138, v97, v97
	v_xor_b32_e32 v141, 0x80000000, v191
	v_xor_b32_e32 v140, 0x80000000, v190
	ds_read_b128 v[188:191], v129 offset:19456
	v_mov_b32_e32 v135, v131
	v_mov_b32_e32 v137, v138
	v_pk_fma_f32 v[98:99], v[98:99], v[128:129], v[140:141] op_sel_hi:[1,0,1]
	v_pk_add_f32 v[134:135], v[134:135], v[136:137]
	v_mul_f32_e32 v136, v105, v105
	v_mul_f32_e32 v139, v98, v98
	v_pk_fma_f32 v[136:137], v[104:105], v[104:105], v[136:137] op_sel_hi:[1,1,0]
	v_mul_f32_e32 v138, v107, v107
	v_mul_f32_e32 v140, v99, v99
	v_mov_b32_e32 v137, v139
	v_pk_fma_f32 v[138:139], v[106:107], v[106:107], v[138:139] op_sel_hi:[1,1,0]
	s_nop 0
	v_mov_b32_e32 v139, v140
	v_pk_add_f32 v[136:137], v[136:137], v[138:139]
	s_nop 0
	v_pk_add_f32 v[134:135], v[134:135], v[136:137]
	v_pk_add_f32 v[134:135], v[134:135], v[134:135] op_sel:[0,1] op_sel_hi:[1,0]
	s_waitcnt lgkmcnt(11)
; template <int DV, int NMAP> ...
;     ...
;             for (int db = 0; db < DV / 16; ++db)
; #pragma unroll
;                 for (int qb = 0; qb < 2; ++qb) { const f32x4 x = o[db][qb] * inv[qb] - xch[(db * 2 + qb) * 64 + lane]; o[db][qb] = x; ss[qb] += (x[0] * x[0] + x[1] * x[1]) + (x[2] * x[2] + x[3] * x[3]); if (qb == 1 && (db & 1)) asm volatile("" ::: "memory"); }
	v_xor_b32_e32 v139, 0x80000000, v195
	v_xor_b32_e32 v138, 0x80000000, v194
	v_pk_fma_f32 v[94:95], v[94:95], v[130:131], v[138:139] op_sel_hi:[1,0,1]
	v_pk_fma_f32 v[92:93], v[92:93], v[130:131], v[192:193] op_sel_hi:[1, 0, 1] neg_lo:[0, 0, 1] neg_hi:[0, 0, 1]
	ds_read_b128 v[192:195], v129 offset:20480
	v_pk_mul_f32 v[136:137], v[94:95], v[94:95]
	v_pk_mul_f32 v[138:139], v[92:93], v[92:93]
	s_nop 0
	v_pk_mov_b32 v[140:141], v[138:139], v[136:137] op_sel:[1,0]
	v_mov_b32_e32 v139, v137
	v_pk_add_f32 v[142:143], v[140:141], v[138:139]
	s_waitcnt lgkmcnt(11)
	v_xor_b32_e32 v139, 0x80000000, v199
	v_xor_b32_e32 v138, 0x80000000, v198
	v_pk_fma_f32 v[90:91], v[90:91], v[128:129], v[138:139] op_sel_hi:[1,0,1]
	v_pk_fma_f32 v[88:89], v[88:89], v[128:129], v[196:197] op_sel_hi:[1, 0, 1] neg_lo:[0, 0, 1] neg_hi:[0, 0, 1]
	ds_read_b128 v[196:199], v129 offset:21504
	v_pk_mul_f32 v[136:137], v[90:91], v[90:91]
	v_pk_mul_f32 v[138:139], v[88:89], v[88:89]
	s_nop 0
	v_pk_mov_b32 v[140:141], v[138:139], v[136:137] op_sel:[1,0]
	v_mov_b32_e32 v139, v137
	v_pk_add_f32 v[136:137], v[140:141], v[138:139]
	v_pk_add_f32 v[136:137], v[136:137], v[136:137] op_sel:[0,1] op_sel_hi:[1,0]
	s_waitcnt lgkmcnt(11)
	v_xor_b32_e32 v141, 0x80000000, v203
	v_xor_b32_e32 v140, 0x80000000, v202
	v_pk_fma_f32 v[86:87], v[86:87], v[130:131], v[140:141] op_sel_hi:[1,0,1]
	v_pk_fma_f32 v[84:85], v[84:85], v[130:131], v[200:201] op_sel_hi:[1, 0, 1] neg_lo:[0, 0, 1] neg_hi:[0, 0, 1]
	ds_read_b128 v[200:203], v129 offset:22528
	s_waitcnt lgkmcnt(11)
	v_xor_b32_e32 v141, 0x80000000, v151
	v_xor_b32_e32 v140, 0x80000000, v150
	v_pk_fma_f32 v[82:83], v[82:83], v[128:129], v[140:141] op_sel_hi:[1,0,1]
	v_pk_fma_f32 v[80:81], v[80:81], v[128:129], v[148:149] op_sel_hi:[1, 0, 1] neg_lo:[0, 0, 1] neg_hi:[0, 0, 1]
	ds_read_b128 v[148:151], v129 offset:23552
	s_waitcnt lgkmcnt(11)
	v_xor_b32_e32 v141, 0x80000000, v163
	v_xor_b32_e32 v140, 0x80000000, v162
	v_pk_fma_f32 v[76:77], v[76:77], v[130:131], v[160:161] op_sel_hi:[1, 0, 1] neg_lo:[0, 0, 1] neg_hi:[0, 0, 1]
	ds_read_b128 v[160:163], v129 offset:24576
	v_pk_fma_f32 v[78:79], v[78:79], v[130:131], v[140:141] op_sel_hi:[1,0,1]
	v_mul_f32_e32 v131, v76, v76
	v_mul_f32_e32 v140, v77, v77
	v_pk_add_f32 v[138:139], v[142:143], v[142:143] op_sel:[0,1] op_sel_hi:[1,0]
	v_mov_b32_e32 v133, v131
	v_mov_b32_e32 v139, v140
	v_pk_add_f32 v[132:133], v[132:133], v[138:139]
	v_mul_f32_e32 v138, v85, v85
	v_mul_f32_e32 v141, v78, v78
	v_pk_fma_f32 v[138:139], v[84:85], v[84:85], v[138:139] op_sel_hi:[1,1,0]
	v_mul_f32_e32 v140, v87, v87
	v_mul_f32_e32 v144, v79, v79
	v_mov_b32_e32 v139, v141
	v_pk_fma_f32 v[140:141], v[86:87], v[86:87], v[140:141] op_sel_hi:[1,1,0]
	s_nop 0
	v_mov_b32_e32 v141, v144
	v_pk_add_f32 v[138:139], v[138:139], v[140:141]
	s_nop 0
	v_pk_add_f32 v[132:133], v[132:133], v[138:139]
	v_pk_add_f32 v[132:133], v[132:133], v[132:133] op_sel:[0,1] op_sel_hi:[1,0]
	s_waitcnt lgkmcnt(11)
	v_pk_fma_f32 v[72:73], v[72:73], v[128:129], v[164:165] op_sel_hi:[1, 0, 1] neg_lo:[0, 0, 1] neg_hi:[0, 0, 1]
	s_nop 0
	v_mul_f32_e32 v131, v72, v72
	v_mul_f32_e32 v138, v73, v73
	v_xor_b32_e32 v141, 0x80000000, v167
	v_xor_b32_e32 v140, 0x80000000, v166
	ds_read_b128 v[164:167], v129 offset:25600
	v_mov_b32_e32 v135, v131
	v_mov_b32_e32 v137, v138
	v_pk_fma_f32 v[74:75], v[74:75], v[128:129], v[140:141] op_sel_hi:[1,0,1]
	v_pk_add_f32 v[134:135], v[134:135], v[136:137]
	v_mul_f32_e32 v136, v81, v81
	v_mul_f32_e32 v139, v74, v74
	v_pk_fma_f32 v[136:137], v[80:81], v[80:81], v[136:137] op_sel_hi:[1,1,0]
	v_mul_f32_e32 v138, v83, v83
	v_mul_f32_e32 v140, v75, v75
	v_mov_b32_e32 v137, v139
	v_pk_fma_f32 v[138:139], v[82:83], v[82:83], v[138:139] op_sel_hi:[1,1,0]
	s_nop 0
	v_mov_b32_e32 v139, v140
	v_pk_add_f32 v[136:137], v[136:137], v[138:139]
	s_nop 0
	v_pk_add_f32 v[134:135], v[134:135], v[136:137]
	v_pk_add_f32 v[134:135], v[134:135], v[134:135] op_sel:[0,1] op_sel_hi:[1,0]
	s_waitcnt lgkmcnt(11)
	v_xor_b32_e32 v139, 0x80000000, v171
	v_xor_b32_e32 v138, 0x80000000, v170
	v_pk_fma_f32 v[70:71], v[70:71], v[130:131], v[138:139] op_sel_hi:[1,0,1]
	v_pk_fma_f32 v[68:69], v[68:69], v[130:131], v[168:169] op_sel_hi:[1, 0, 1] neg_lo:[0, 0, 1] neg_hi:[0, 0, 1]
	ds_read_b128 v[168:171], v129 offset:26624
	v_pk_mul_f32 v[136:137], v[70:71], v[70:71]
	v_pk_mul_f32 v[138:139], v[68:69], v[68:69]
	s_nop 0
	v_pk_mov_b32 v[140:141], v[138:139], v[136:137] op_sel:[1,0]
	v_mov_b32_e32 v139, v137
	v_pk_add_f32 v[142:143], v[140:141], v[138:139]
	s_waitcnt lgkmcnt(11)
	v_xor_b32_e32 v139, 0x80000000, v175
	v_xor_b32_e32 v138, 0x80000000, v174
	v_pk_fma_f32 v[66:67], v[66:67], v[128:129], v[138:139] op_sel_hi:[1,0,1]
	v_pk_fma_f32 v[64:65], v[64:65], v[128:129], v[172:173] op_sel_hi:[1, 0, 1] neg_lo:[0, 0, 1] neg_hi:[0, 0, 1]
	ds_read_b128 v[172:175], v129 offset:27648
	v_pk_mul_f32 v[136:137], v[66:67], v[66:67]
	v_pk_mul_f32 v[138:139], v[64:65], v[64:65]
	s_nop 0
	v_pk_mov_b32 v[140:141], v[138:139], v[136:137] op_sel:[1,0]
	v_mov_b32_e32 v139, v137
	v_pk_add_f32 v[136:137], v[140:141], v[138:139]
	v_pk_add_f32 v[136:137], v[136:137], v[136:137] op_sel:[0,1] op_sel_hi:[1,0]
	s_waitcnt lgkmcnt(11)
	v_xor_b32_e32 v141, 0x80000000, v179
	v_xor_b32_e32 v140, 0x80000000, v178
	v_pk_fma_f32 v[62:63], v[62:63], v[130:131], v[140:141] op_sel_hi:[1,0,1]
	v_pk_fma_f32 v[60:61], v[60:61], v[130:131], v[176:177] op_sel_hi:[1, 0, 1] neg_lo:[0, 0, 1] neg_hi:[0, 0, 1]
	ds_read_b128 v[176:179], v129 offset:28672
	s_waitcnt lgkmcnt(11)
; template <int DV, int NMAP> ...
;     ...
;             for (int db = 0; db < DV / 16; ++db)
; #pragma unroll
;                 for (int qb = 0; qb < 2; ++qb) { const f32x4 x = o[db][qb] * inv[qb] - xch[(db * 2 + qb) * 64 + lane]; o[db][qb] = x; ss[qb] += (x[0] * x[0] + x[1] * x[1]) + (x[2] * x[2] + x[3] * x[3]); if (qb == 1 && (db & 1)) asm volatile("" ::: "memory"); }
	v_xor_b32_e32 v141, 0x80000000, v183
	v_xor_b32_e32 v140, 0x80000000, v182
	v_pk_fma_f32 v[58:59], v[58:59], v[128:129], v[140:141] op_sel_hi:[1,0,1]
	v_pk_fma_f32 v[56:57], v[56:57], v[128:129], v[180:181] op_sel_hi:[1, 0, 1] neg_lo:[0, 0, 1] neg_hi:[0, 0, 1]
	ds_read_b128 v[180:183], v129 offset:29696
	s_waitcnt lgkmcnt(11)
	v_xor_b32_e32 v141, 0x80000000, v187
	v_xor_b32_e32 v140, 0x80000000, v186
	v_pk_fma_f32 v[52:53], v[52:53], v[130:131], v[184:185] op_sel_hi:[1, 0, 1] neg_lo:[0, 0, 1] neg_hi:[0, 0, 1]
	ds_read_b128 v[184:187], v129 offset:30720
	v_pk_fma_f32 v[54:55], v[54:55], v[130:131], v[140:141] op_sel_hi:[1,0,1]
	v_mul_f32_e32 v131, v52, v52
	v_mul_f32_e32 v140, v53, v53
	v_pk_add_f32 v[138:139], v[142:143], v[142:143] op_sel:[0,1] op_sel_hi:[1,0]
	v_mov_b32_e32 v133, v131
	v_mov_b32_e32 v139, v140
	v_pk_add_f32 v[132:133], v[132:133], v[138:139]
	v_mul_f32_e32 v138, v61, v61
	v_mul_f32_e32 v141, v54, v54
	v_pk_fma_f32 v[138:139], v[60:61], v[60:61], v[138:139] op_sel_hi:[1,1,0]
	v_mul_f32_e32 v140, v63, v63
	v_mul_f32_e32 v144, v55, v55
	v_mov_b32_e32 v139, v141
	v_pk_fma_f32 v[140:141], v[62:63], v[62:63], v[140:141] op_sel_hi:[1,1,0]
	s_nop 0
	v_mov_b32_e32 v141, v144
	v_pk_add_f32 v[138:139], v[138:139], v[140:141]
	s_nop 0
	v_pk_add_f32 v[132:133], v[132:133], v[138:139]
	v_pk_add_f32 v[132:133], v[132:133], v[132:133] op_sel:[0,1] op_sel_hi:[1,0]
	s_waitcnt lgkmcnt(11)
	v_pk_fma_f32 v[48:49], v[48:49], v[128:129], v[188:189] op_sel_hi:[1, 0, 1] neg_lo:[0, 0, 1] neg_hi:[0, 0, 1]
	s_nop 0
	v_mul_f32_e32 v131, v48, v48
	v_mul_f32_e32 v138, v49, v49
	v_xor_b32_e32 v141, 0x80000000, v191
	v_xor_b32_e32 v140, 0x80000000, v190
	ds_read_b128 v[188:191], v129 offset:31744
	v_mov_b32_e32 v135, v131
	v_mov_b32_e32 v137, v138
	v_pk_fma_f32 v[50:51], v[50:51], v[128:129], v[140:141] op_sel_hi:[1,0,1]
	v_pk_add_f32 v[134:135], v[134:135], v[136:137]
	v_mul_f32_e32 v136, v57, v57
	v_mul_f32_e32 v139, v50, v50
	v_pk_fma_f32 v[136:137], v[56:57], v[56:57], v[136:137] op_sel_hi:[1,1,0]
	v_mul_f32_e32 v138, v59, v59
	v_mul_f32_e32 v140, v51, v51
	v_mov_b32_e32 v137, v139
	v_pk_fma_f32 v[138:139], v[58:59], v[58:59], v[138:139] op_sel_hi:[1,1,0]
	s_nop 0
	v_mov_b32_e32 v139, v140
	v_pk_add_f32 v[136:137], v[136:137], v[138:139]
	s_nop 0
	v_pk_add_f32 v[134:135], v[134:135], v[136:137]
	s_waitcnt lgkmcnt(11)
	v_xor_b32_e32 v139, 0x80000000, v195
	v_xor_b32_e32 v138, 0x80000000, v194
	v_pk_fma_f32 v[46:47], v[46:47], v[130:131], v[138:139] op_sel_hi:[1,0,1]
	v_pk_fma_f32 v[44:45], v[44:45], v[130:131], v[192:193] op_sel_hi:[1, 0, 1] neg_lo:[0, 0, 1] neg_hi:[0, 0, 1]
	v_pk_mul_f32 v[136:137], v[46:47], v[46:47]
	v_pk_mul_f32 v[138:139], v[44:45], v[44:45]
	s_nop 0
	v_pk_mov_b32 v[140:141], v[138:139], v[136:137] op_sel:[1,0]
	v_mov_b32_e32 v139, v137
	v_pk_add_f32 v[142:143], v[140:141], v[138:139]
	s_waitcnt lgkmcnt(10)
	v_xor_b32_e32 v139, 0x80000000, v199
	v_xor_b32_e32 v138, 0x80000000, v198
	v_pk_fma_f32 v[42:43], v[42:43], v[128:129], v[138:139] op_sel_hi:[1,0,1]
	v_pk_fma_f32 v[40:41], v[40:41], v[128:129], v[196:197] op_sel_hi:[1, 0, 1] neg_lo:[0, 0, 1] neg_hi:[0, 0, 1]
	v_pk_mul_f32 v[136:137], v[42:43], v[42:43]
	v_pk_mul_f32 v[138:139], v[40:41], v[40:41]
	s_nop 0
	v_pk_mov_b32 v[140:141], v[138:139], v[136:137] op_sel:[1,0]
	v_mov_b32_e32 v139, v137
	v_pk_add_f32 v[136:137], v[140:141], v[138:139]
	s_waitcnt lgkmcnt(9)
	v_xor_b32_e32 v141, 0x80000000, v203
	v_xor_b32_e32 v140, 0x80000000, v202
	v_pk_fma_f32 v[38:39], v[38:39], v[130:131], v[140:141] op_sel_hi:[1,0,1]
	v_pk_fma_f32 v[36:37], v[36:37], v[130:131], v[200:201] op_sel_hi:[1, 0, 1] neg_lo:[0, 0, 1] neg_hi:[0, 0, 1]
	s_waitcnt lgkmcnt(8)
	v_xor_b32_e32 v141, 0x80000000, v151
	v_xor_b32_e32 v140, 0x80000000, v150
	v_pk_fma_f32 v[34:35], v[34:35], v[128:129], v[140:141] op_sel_hi:[1,0,1]
	v_pk_fma_f32 v[32:33], v[32:33], v[128:129], v[148:149] op_sel_hi:[1, 0, 1] neg_lo:[0, 0, 1] neg_hi:[0, 0, 1]
	s_waitcnt lgkmcnt(7)
	v_xor_b32_e32 v141, 0x80000000, v163
	v_xor_b32_e32 v140, 0x80000000, v162
	v_pk_fma_f32 v[28:29], v[28:29], v[130:131], v[160:161] op_sel_hi:[1, 0, 1] neg_lo:[0, 0, 1] neg_hi:[0, 0, 1]
	v_pk_fma_f32 v[30:31], v[30:31], v[130:131], v[140:141] op_sel_hi:[1,0,1]
	v_mul_f32_e32 v131, v28, v28
	v_mul_f32_e32 v140, v29, v29
	v_pk_add_f32 v[138:139], v[142:143], v[142:143] op_sel:[0,1] op_sel_hi:[1,0]
	v_mov_b32_e32 v133, v131
	v_mov_b32_e32 v139, v140
	v_pk_add_f32 v[132:133], v[132:133], v[138:139]
	v_mul_f32_e32 v138, v37, v37
	v_mul_f32_e32 v141, v30, v30
	v_pk_fma_f32 v[138:139], v[36:37], v[36:37], v[138:139] op_sel_hi:[1,1,0]
	v_mul_f32_e32 v140, v39, v39
	v_mul_f32_e32 v144, v31, v31
	v_mov_b32_e32 v139, v141
	v_pk_fma_f32 v[140:141], v[38:39], v[38:39], v[140:141] op_sel_hi:[1,1,0]
	s_nop 0
	v_mov_b32_e32 v141, v144
	v_pk_add_f32 v[138:139], v[138:139], v[140:141]
	v_pk_add_f32 v[138:139], v[132:133], v[138:139]
	s_waitcnt lgkmcnt(6)
	v_xor_b32_e32 v133, 0x80000000, v167
	v_xor_b32_e32 v132, 0x80000000, v166
	v_pk_fma_f32 v[24:25], v[24:25], v[128:129], v[164:165] op_sel_hi:[1, 0, 1] neg_lo:[0, 0, 1] neg_hi:[0, 0, 1]
	v_pk_fma_f32 v[26:27], v[26:27], v[128:129], v[132:133] op_sel_hi:[1,0,1]
	v_mul_f32_e32 v131, v24, v24
	v_mul_f32_e32 v140, v25, v25
	v_pk_add_f32 v[132:133], v[134:135], v[134:135] op_sel:[0,1] op_sel_hi:[1,0]
	v_pk_add_f32 v[134:135], v[136:137], v[136:137] op_sel:[0,1] op_sel_hi:[1,0]
	v_mov_b32_e32 v133, v131
	v_mov_b32_e32 v135, v140
	v_pk_add_f32 v[132:133], v[132:133], v[134:135]
	v_mul_f32_e32 v134, v33, v33
	v_mul_f32_e32 v136, v35, v35
	v_mul_f32_e32 v141, v26, v26
	v_mul_f32_e32 v142, v27, v27
	v_pk_fma_f32 v[134:135], v[32:33], v[32:33], v[134:135] op_sel_hi:[1,1,0]
	v_pk_fma_f32 v[136:137], v[34:35], v[34:35], v[136:137] op_sel_hi:[1,1,0]
	v_mov_b32_e32 v135, v141
	v_mov_b32_e32 v137, v142
	v_pk_add_f32 v[134:135], v[134:135], v[136:137]
	s_nop 0
	v_pk_add_f32 v[136:137], v[132:133], v[134:135]
	s_waitcnt lgkmcnt(5)
; template <int DV, int NMAP> ...
;     ...
;             for (int db = 0; db < DV / 16; ++db)
; #pragma unroll
;                 for (int qb = 0; qb < 2; ++qb) { const f32x4 x = o[db][qb] * inv[qb] - xch[(db * 2 + qb) * 64 + lane]; o[db][qb] = x; ss[qb] += (x[0] * x[0] + x[1] * x[1]) + (x[2] * x[2] + x[3] * x[3]); if (qb == 1 && (db & 1)) asm volatile("" ::: "memory"); }
; #pragma unroll
;             for (int qb = 0; qb < 2; ++qb) { float v = ss[qb]; v += __shfl_xor(v, 16); v += __shfl_xor(v, 32); ss[qb] = outscale / sqrtf(v * (1.0f / DV) + RMS_EPS); }
; #pragma unroll
;             for (int db = 0; db < DV / 16; ++db) { const f32x4 g = *(const f32x4*)(subg + 16 * db + 4 * fq);
	v_xor_b32_e32 v135, 0x80000000, v171
	v_xor_b32_e32 v134, 0x80000000, v170
	v_pk_fma_f32 v[22:23], v[22:23], v[130:131], v[134:135] op_sel_hi:[1,0,1]
	v_pk_fma_f32 v[20:21], v[20:21], v[130:131], v[168:169] op_sel_hi:[1, 0, 1] neg_lo:[0, 0, 1] neg_hi:[0, 0, 1]
	v_pk_mul_f32 v[132:133], v[22:23], v[22:23]
	v_pk_mul_f32 v[134:135], v[20:21], v[20:21]
	s_nop 0
	v_pk_mov_b32 v[140:141], v[134:135], v[132:133] op_sel:[1,0]
	v_mov_b32_e32 v135, v133
	v_pk_add_f32 v[146:147], v[140:141], v[134:135]
	s_waitcnt lgkmcnt(4)
	v_xor_b32_e32 v133, 0x80000000, v175
	v_xor_b32_e32 v132, 0x80000000, v174
	v_pk_fma_f32 v[132:133], v[14:15], v[128:129], v[132:133] op_sel_hi:[1,0,1]
	v_pk_fma_f32 v[134:135], v[12:13], v[128:129], v[172:173] op_sel_hi:[1, 0, 1] neg_lo:[0, 0, 1] neg_hi:[0, 0, 1]
	v_pk_mul_f32 v[12:13], v[132:133], v[132:133]
	v_pk_mul_f32 v[14:15], v[134:135], v[134:135]
	s_nop 0
	v_pk_mov_b32 v[140:141], v[14:15], v[12:13] op_sel:[1,0]
	v_mov_b32_e32 v15, v13
	s_waitcnt lgkmcnt(3)
	v_xor_b32_e32 v13, 0x80000000, v179
	v_xor_b32_e32 v12, 0x80000000, v178
	v_pk_add_f32 v[140:141], v[140:141], v[14:15]
	v_pk_fma_f32 v[12:13], v[18:19], v[130:131], v[12:13] op_sel_hi:[1,0,1]
	v_pk_fma_f32 v[14:15], v[16:17], v[130:131], v[176:177] op_sel_hi:[1, 0, 1] neg_lo:[0, 0, 1] neg_hi:[0, 0, 1]
	s_waitcnt lgkmcnt(2)
	v_xor_b32_e32 v19, 0x80000000, v183
	v_xor_b32_e32 v18, 0x80000000, v182
	v_pk_fma_f32 v[10:11], v[10:11], v[128:129], v[18:19] op_sel_hi:[1,0,1]
	v_pk_fma_f32 v[8:9], v[8:9], v[128:129], v[180:181] op_sel_hi:[1, 0, 1] neg_lo:[0, 0, 1] neg_hi:[0, 0, 1]
	s_waitcnt lgkmcnt(1)
	v_xor_b32_e32 v19, 0x80000000, v187
	v_xor_b32_e32 v18, 0x80000000, v186
	v_pk_fma_f32 v[4:5], v[4:5], v[130:131], v[184:185] op_sel_hi:[1, 0, 1] neg_lo:[0, 0, 1] neg_hi:[0, 0, 1]
	v_pk_fma_f32 v[6:7], v[6:7], v[130:131], v[18:19] op_sel_hi:[1,0,1]
	v_mul_f32_e32 v18, v4, v4
	v_pk_add_f32 v[16:17], v[138:139], v[138:139] op_sel:[0,1] op_sel_hi:[1,0]
	v_mul_f32_e32 v130, v5, v5
	v_mov_b32_e32 v17, v18
	v_pk_add_f32 v[18:19], v[146:147], v[146:147] op_sel:[0,1] op_sel_hi:[1,0]
	v_mul_f32_e32 v131, v6, v6
	v_mov_b32_e32 v19, v130
	v_pk_add_f32 v[16:17], v[16:17], v[18:19]
	v_mul_f32_e32 v18, v15, v15
	v_pk_fma_f32 v[18:19], v[14:15], v[14:15], v[18:19] op_sel_hi:[1,1,0]
	v_mul_f32_e32 v130, v13, v13
	v_mul_f32_e32 v142, v7, v7
	v_mov_b32_e32 v19, v131
	v_pk_fma_f32 v[130:131], v[12:13], v[12:13], v[130:131] op_sel_hi:[1,1,0]
	s_nop 0
	v_mov_b32_e32 v131, v142
	v_pk_add_f32 v[18:19], v[18:19], v[130:131]
	s_nop 0
	v_pk_add_f32 v[16:17], v[16:17], v[18:19]
	s_waitcnt lgkmcnt(0)
	v_pk_fma_f32 v[18:19], v[0:1], v[128:129], v[188:189] op_sel_hi:[1, 0, 1] neg_lo:[0, 0, 1] neg_hi:[0, 0, 1]
	v_add_f32_e32 v130, v16, v17
	v_xor_b32_e32 v17, 0x80000000, v191
	v_xor_b32_e32 v16, 0x80000000, v190
	v_lshlrev_b32_e32 v206, 4, v236
	global_load_dwordx4 v[160:163], v206, s[46:47]
	global_load_dwordx4 v[164:167], v206, s[46:47] offset:64
	global_load_dwordx4 v[168:171], v206, s[46:47] offset:128
	global_load_dwordx4 v[172:175], v206, s[46:47] offset:192
	global_load_dwordx4 v[176:179], v206, s[46:47] offset:256
	global_load_dwordx4 v[180:183], v206, s[46:47] offset:320
	global_load_dwordx4 v[184:187], v206, s[46:47] offset:384
	global_load_dwordx4 v[188:191], v206, s[46:47] offset:448
	global_load_dwordx4 v[192:195], v206, s[46:47] offset:512
	global_load_dwordx4 v[196:199], v206, s[46:47] offset:576
	global_load_dwordx4 v[200:203], v206, s[46:47] offset:640
	global_load_dwordx4 v[148:151], v206, s[46:47] offset:704
	global_load_dwordx4 v[152:155], v206, s[46:47] offset:768
	global_load_dwordx4 v[240:243], v206, s[46:47] offset:832
	global_load_dwordx4 v[244:247], v206, s[46:47] offset:896
	global_load_dwordx4 v[248:251], v206, s[46:47] offset:960
	v_pk_fma_f32 v[16:17], v[2:3], v[128:129], v[16:17] op_sel_hi:[1,0,1]
	v_mul_f32_e32 v2, v18, v18
	v_pk_add_f32 v[0:1], v[136:137], v[136:137] op_sel:[0,1] op_sel_hi:[1,0]
	v_mul_f32_e32 v128, v19, v19
	v_mov_b32_e32 v1, v2
	v_pk_add_f32 v[2:3], v[140:141], v[140:141] op_sel:[0,1] op_sel_hi:[1,0]
	v_mul_f32_e32 v129, v16, v16
	v_mov_b32_e32 v3, v128
	v_pk_add_f32 v[0:1], v[0:1], v[2:3]
	v_mul_f32_e32 v2, v9, v9
	v_pk_fma_f32 v[2:3], v[8:9], v[8:9], v[2:3] op_sel_hi:[1,1,0]
	v_mul_f32_e32 v128, v11, v11
	v_mul_f32_e32 v131, v17, v17
	v_mov_b32_e32 v3, v129
	v_pk_fma_f32 v[128:129], v[10:11], v[10:11], v[128:129] op_sel_hi:[1,1,0]
	s_nop 0
	v_mov_b32_e32 v129, v131
	v_pk_add_f32 v[2:3], v[2:3], v[128:129]
	s_nop 0
	v_pk_add_f32 v[0:1], v[0:1], v[2:3]
	s_nop 0
	v_add_f32_e32 v0, v0, v1
	ds_bpermute_b32 v1, v231, v130
	s_waitcnt lgkmcnt(0)
	v_add_f32_e32 v1, v130, v1
	ds_bpermute_b32 v2, v232, v1
	s_waitcnt lgkmcnt(0)
	v_add_f32_e32 v1, v1, v2
	v_fmamk_f32 v1, v1, 0x3b800000, v226
	v_cmp_gt_f32_e32 vcc, s93, v1
	v_mul_f32_e32 v2, 0x4f800000, v1
	s_nop 0
	v_cndmask_b32_e32 v1, v1, v2, vcc
	v_sqrt_f32_e32 v2, v1
	s_nop 0
	v_add_u32_e32 v3, -1, v2
	v_fma_f32 v128, -v3, v2, v1
	v_cmp_ge_f32_e64 s[38:39], 0, v128
	v_add_u32_e32 v128, 1, v2
	s_nop 0
	v_cndmask_b32_e64 v3, v2, v3, s[38:39]
	v_fma_f32 v2, -v128, v2, v1
	v_cmp_lt_f32_e64 s[38:39], 0, v2
	s_nop 1
	v_cndmask_b32_e64 v2, v3, v128, s[38:39]
	v_mul_f32_e32 v3, 0x37800000, v2
	v_cndmask_b32_e32 v2, v2, v3, vcc
	v_cmp_class_f32_e32 vcc, v1, v227
	s_nop 1
	v_cndmask_b32_e32 v1, v2, v1, vcc
	v_div_scale_f32 v2, s[4:5], v1, v1, v234
	v_rcp_f32_e32 v3, v2
	s_nop 0
	v_fma_f32 v128, -v2, v3, 1.0
	v_fmac_f32_e32 v3, v128, v3
	v_div_scale_f32 v128, vcc, v234, v1, v234
	v_mul_f32_e32 v129, v128, v3
	v_fma_f32 v130, -v2, v129, v128
	v_fmac_f32_e32 v129, v130, v3
	v_fma_f32 v2, -v2, v129, v128
	v_div_fmas_f32 v2, v2, v3, v129
	v_div_fixup_f32 v130, v2, v1, v234
	ds_bpermute_b32 v1, v231, v0
	s_waitcnt lgkmcnt(0)
; __device__ __forceinline__ unsigned cvt_pk_bf16(float lo, float hi) { unsigned r; asm volatile("v_cvt_pk_bf16_f32 %0, %1, %2" : "=v"(r) : "v"(lo), "v"(hi)); return r; }
; template <int DV, int NMAP> ...
;     ...
;             for (int qb = 0; qb < 2; ++qb) { float v = ss[qb]; v += __shfl_xor(v, 16); v += __shfl_xor(v, 32); ss[qb] = outscale / sqrtf(v * (1.0f / DV) + RMS_EPS); }
; #pragma unroll
;             for (int db = 0; db < DV / 16; ++db) { const f32x4 g = *(const f32x4*)(subg + 16 * db + 4 * fq);
; #pragma unroll
;                 for (int qb = 0; qb < 2; ++qb) { const f32x4 v = o[db][qb] * g * ss[qb]; v2u w; w.x = pg8::cvt_pk_bf16(v[0], v[1]); w.y = pg8::cvt_pk_bf16(v[2], v[3]);
;                     *(v2u*)(O + (size_t)(q0w + 16 * qb + fr) * DM + vrow0 + 16 * db + 4 * fq) = w; } }
	v_add_f32_e32 v0, v0, v1
	ds_bpermute_b32 v1, v232, v0
	s_waitcnt lgkmcnt(0)
	v_add_f32_e32 v0, v0, v1
	v_fmamk_f32 v0, v0, 0x3b800000, v226
	v_cmp_gt_f32_e32 vcc, s93, v0
	v_mul_f32_e32 v1, 0x4f800000, v0
	s_nop 0
	v_cndmask_b32_e32 v0, v0, v1, vcc
	v_sqrt_f32_e32 v1, v0
	s_nop 0
	v_add_u32_e32 v2, -1, v1
	v_fma_f32 v3, -v2, v1, v0
	v_cmp_ge_f32_e64 s[38:39], 0, v3
	v_add_u32_e32 v3, 1, v1
	s_nop 0
	v_cndmask_b32_e64 v2, v1, v2, s[38:39]
	v_fma_f32 v1, -v3, v1, v0
	v_cmp_lt_f32_e64 s[38:39], 0, v1
	s_nop 1
	v_cndmask_b32_e64 v1, v2, v3, s[38:39]
	v_mul_f32_e32 v2, 0x37800000, v1
	v_cndmask_b32_e32 v1, v1, v2, vcc
	v_cmp_class_f32_e32 vcc, v0, v227
	s_nop 1
	v_cndmask_b32_e32 v0, v1, v0, vcc
	v_div_scale_f32 v1, s[4:5], v0, v0, v234
	v_rcp_f32_e32 v2, v1
	s_lshl_b32 s4, s36, 1
	s_add_u32 s4, s98, s4
	s_addc_u32 s5, s99, 0
	v_fma_f32 v3, -v1, v2, 1.0
	v_fmac_f32_e32 v2, v3, v2
	v_div_scale_f32 v3, vcc, v234, v0, v234
	v_mul_f32_e32 v128, v3, v2
	v_fma_f32 v129, -v1, v128, v3
	v_fmac_f32_e32 v128, v129, v2
	v_fma_f32 v1, -v1, v128, v3
	v_div_fmas_f32 v1, v1, v2, v128
	v_lshlrev_b32_e32 v129, 4, v236
	v_div_fixup_f32 v128, v1, v0, v234
	v_lshl_add_u64 v[136:137], s[4:5], 0, v[204:205]
	v_lshlrev_b32_e32 v204, 12, v235
	s_waitcnt vmcnt(0)
	v_pk_mul_f32 v[124:125], v[124:125], v[162:163]
	v_pk_mul_f32 v[126:127], v[126:127], v[160:161]
	v_pk_mul_f32 v[124:125], v[124:125], v[130:131] op_sel_hi:[1, 0]
	v_pk_mul_f32 v[126:127], v[126:127], v[130:131] op_sel_hi:[1, 0]
	v_pk_mul_f32 v[0:1], v[120:121], v[160:161]
	v_cvt_pk_bf16_f32 v126, v126, v127
	v_cvt_pk_bf16_f32 v127, v124, v125
	v_lshl_add_u64 v[124:125], v[136:137], 0, v[204:205]
	v_pk_mul_f32 v[2:3], v[122:123], v[162:163]
	v_pk_mul_f32 v[0:1], v[0:1], v[128:129] op_sel_hi:[1, 0]
	v_or_b32_e32 v204, 0x10000, v204
	global_store_dwordx2 v[124:125], v[126:127], off
	v_pk_mul_f32 v[2:3], v[2:3], v[128:129] op_sel_hi:[1, 0]
	v_cvt_pk_bf16_f32 v120, v0, v1
	v_lshl_add_u64 v[0:1], v[136:137], 0, v[204:205]
	v_cvt_pk_bf16_f32 v121, v2, v3
	global_store_dwordx2 v[0:1], v[120:121], off
	v_pk_mul_f32 v[2:3], v[118:119], v[166:167]
	v_pk_mul_f32 v[116:117], v[116:117], v[164:165]
	v_pk_mul_f32 v[2:3], v[2:3], v[130:131] op_sel_hi:[1, 0]
	v_pk_mul_f32 v[116:117], v[116:117], v[130:131] op_sel_hi:[1, 0]
	v_pk_mul_f32 v[112:113], v[112:113], v[164:165]
	v_cvt_pk_bf16_f32 v116, v116, v117
	v_cvt_pk_bf16_f32 v117, v2, v3
	v_pk_mul_f32 v[2:3], v[114:115], v[166:167]
	v_pk_mul_f32 v[112:113], v[112:113], v[128:129] op_sel_hi:[1, 0]
	global_store_dwordx2 v[124:125], v[116:117], off offset:32
	v_pk_mul_f32 v[2:3], v[2:3], v[128:129] op_sel_hi:[1, 0]
	v_cvt_pk_bf16_f32 v112, v112, v113
	s_nop 0
	v_cvt_pk_bf16_f32 v113, v2, v3
	global_store_dwordx2 v[0:1], v[112:113], off offset:32
	v_pk_mul_f32 v[2:3], v[110:111], v[170:171]
	v_pk_mul_f32 v[108:109], v[108:109], v[168:169]
	v_pk_mul_f32 v[2:3], v[130:131], v[2:3] op_sel_hi:[0, 1]
	v_pk_mul_f32 v[108:109], v[130:131], v[108:109] op_sel_hi:[0, 1]
	v_pk_mul_f32 v[104:105], v[104:105], v[168:169]
	v_cvt_pk_bf16_f32 v108, v108, v109
	v_cvt_pk_bf16_f32 v109, v2, v3
	v_pk_mul_f32 v[2:3], v[106:107], v[170:171]
	v_pk_mul_f32 v[104:105], v[128:129], v[104:105] op_sel_hi:[0, 1]
	global_store_dwordx2 v[124:125], v[108:109], off offset:64
	v_pk_mul_f32 v[2:3], v[128:129], v[2:3] op_sel_hi:[0, 1]
	v_cvt_pk_bf16_f32 v104, v104, v105
	v_cvt_pk_bf16_f32 v105, v2, v3
	global_store_dwordx2 v[0:1], v[104:105], off offset:64
	v_pk_mul_f32 v[2:3], v[102:103], v[174:175]
	v_pk_mul_f32 v[100:101], v[100:101], v[172:173]
	v_pk_mul_f32 v[2:3], v[130:131], v[2:3] op_sel_hi:[0, 1]
	v_pk_mul_f32 v[100:101], v[130:131], v[100:101] op_sel_hi:[0, 1]
	v_pk_mul_f32 v[96:97], v[96:97], v[172:173]
	v_cvt_pk_bf16_f32 v100, v100, v101
	v_cvt_pk_bf16_f32 v101, v2, v3
	v_pk_mul_f32 v[2:3], v[98:99], v[174:175]
	v_pk_mul_f32 v[96:97], v[128:129], v[96:97] op_sel_hi:[0, 1]
	global_store_dwordx2 v[124:125], v[100:101], off offset:96
	v_pk_mul_f32 v[2:3], v[128:129], v[2:3] op_sel_hi:[0, 1]
	v_cvt_pk_bf16_f32 v96, v96, v97
	v_cvt_pk_bf16_f32 v97, v2, v3
	global_store_dwordx2 v[0:1], v[96:97], off offset:96
	v_pk_mul_f32 v[2:3], v[94:95], v[178:179]
	v_pk_mul_f32 v[92:93], v[92:93], v[176:177]
	v_pk_mul_f32 v[2:3], v[130:131], v[2:3] op_sel_hi:[0, 1]
	v_pk_mul_f32 v[92:93], v[130:131], v[92:93] op_sel_hi:[0, 1]
	v_pk_mul_f32 v[88:89], v[88:89], v[176:177]
	v_cvt_pk_bf16_f32 v92, v92, v93
	v_cvt_pk_bf16_f32 v93, v2, v3
	v_pk_mul_f32 v[2:3], v[90:91], v[178:179]
	v_pk_mul_f32 v[88:89], v[128:129], v[88:89] op_sel_hi:[0, 1]
	global_store_dwordx2 v[124:125], v[92:93], off offset:128
	v_pk_mul_f32 v[2:3], v[128:129], v[2:3] op_sel_hi:[0, 1]
	v_cvt_pk_bf16_f32 v88, v88, v89
	v_cvt_pk_bf16_f32 v89, v2, v3
	global_store_dwordx2 v[0:1], v[88:89], off offset:128
	v_pk_mul_f32 v[2:3], v[86:87], v[182:183]
	v_pk_mul_f32 v[84:85], v[84:85], v[180:181]
	v_pk_mul_f32 v[2:3], v[130:131], v[2:3] op_sel_hi:[0, 1]
	v_pk_mul_f32 v[84:85], v[130:131], v[84:85] op_sel_hi:[0, 1]
	v_pk_mul_f32 v[80:81], v[80:81], v[180:181]
	v_cvt_pk_bf16_f32 v84, v84, v85
	v_cvt_pk_bf16_f32 v85, v2, v3
	v_pk_mul_f32 v[2:3], v[82:83], v[182:183]
	v_pk_mul_f32 v[80:81], v[128:129], v[80:81] op_sel_hi:[0, 1]
	global_store_dwordx2 v[124:125], v[84:85], off offset:160
	v_pk_mul_f32 v[2:3], v[128:129], v[2:3] op_sel_hi:[0, 1]
	v_cvt_pk_bf16_f32 v80, v80, v81
	v_cvt_pk_bf16_f32 v81, v2, v3
	global_store_dwordx2 v[0:1], v[80:81], off offset:160
	v_pk_mul_f32 v[2:3], v[78:79], v[186:187]
	v_pk_mul_f32 v[76:77], v[76:77], v[184:185]
	v_pk_mul_f32 v[2:3], v[130:131], v[2:3] op_sel_hi:[0, 1]
	v_pk_mul_f32 v[76:77], v[130:131], v[76:77] op_sel_hi:[0, 1]
; __device__ __forceinline__ unsigned cvt_pk_bf16(float lo, float hi) { unsigned r; asm volatile("v_cvt_pk_bf16_f32 %0, %1, %2" : "=v"(r) : "v"(lo), "v"(hi)); return r; }
; template <int DV, int NMAP> ...
;     ...
;             for (int db = 0; db < DV / 16; ++db) { const f32x4 g = *(const f32x4*)(subg + 16 * db + 4 * fq);
; #pragma unroll
;                 for (int qb = 0; qb < 2; ++qb) { const f32x4 v = o[db][qb] * g * ss[qb]; v2u w; w.x = pg8::cvt_pk_bf16(v[0], v[1]); w.y = pg8::cvt_pk_bf16(v[2], v[3]);
;                     *(v2u*)(O + (size_t)(q0w + 16 * qb + fr) * DM + vrow0 + 16 * db + 4 * fq) = w; } }
	v_pk_mul_f32 v[72:73], v[72:73], v[184:185]
	v_cvt_pk_bf16_f32 v76, v76, v77
	v_cvt_pk_bf16_f32 v77, v2, v3
	v_pk_mul_f32 v[2:3], v[74:75], v[186:187]
	v_pk_mul_f32 v[72:73], v[128:129], v[72:73] op_sel_hi:[0, 1]
	global_store_dwordx2 v[124:125], v[76:77], off offset:192
	v_pk_mul_f32 v[2:3], v[128:129], v[2:3] op_sel_hi:[0, 1]
	v_cvt_pk_bf16_f32 v72, v72, v73
	v_cvt_pk_bf16_f32 v73, v2, v3
	global_store_dwordx2 v[0:1], v[72:73], off offset:192
	v_pk_mul_f32 v[2:3], v[70:71], v[190:191]
	v_pk_mul_f32 v[68:69], v[68:69], v[188:189]
	v_pk_mul_f32 v[2:3], v[130:131], v[2:3] op_sel_hi:[0, 1]
	v_pk_mul_f32 v[68:69], v[130:131], v[68:69] op_sel_hi:[0, 1]
	v_pk_mul_f32 v[64:65], v[64:65], v[188:189]
	v_cvt_pk_bf16_f32 v68, v68, v69
	v_cvt_pk_bf16_f32 v69, v2, v3
	v_pk_mul_f32 v[2:3], v[66:67], v[190:191]
	v_pk_mul_f32 v[64:65], v[128:129], v[64:65] op_sel_hi:[0, 1]
	global_store_dwordx2 v[124:125], v[68:69], off offset:224
	v_pk_mul_f32 v[2:3], v[128:129], v[2:3] op_sel_hi:[0, 1]
	v_cvt_pk_bf16_f32 v64, v64, v65
	v_cvt_pk_bf16_f32 v65, v2, v3
	global_store_dwordx2 v[0:1], v[64:65], off offset:224
	v_pk_mul_f32 v[2:3], v[62:63], v[194:195]
	v_pk_mul_f32 v[60:61], v[60:61], v[192:193]
	v_pk_mul_f32 v[2:3], v[130:131], v[2:3] op_sel_hi:[0, 1]
	v_pk_mul_f32 v[60:61], v[130:131], v[60:61] op_sel_hi:[0, 1]
	v_pk_mul_f32 v[56:57], v[56:57], v[192:193]
	v_cvt_pk_bf16_f32 v60, v60, v61
	v_cvt_pk_bf16_f32 v61, v2, v3
	v_pk_mul_f32 v[2:3], v[58:59], v[194:195]
	v_pk_mul_f32 v[56:57], v[128:129], v[56:57] op_sel_hi:[0, 1]
	global_store_dwordx2 v[124:125], v[60:61], off offset:256
	v_pk_mul_f32 v[2:3], v[128:129], v[2:3] op_sel_hi:[0, 1]
	v_cvt_pk_bf16_f32 v56, v56, v57
	v_cvt_pk_bf16_f32 v57, v2, v3
	global_store_dwordx2 v[0:1], v[56:57], off offset:256
	v_pk_mul_f32 v[2:3], v[54:55], v[198:199]
	v_pk_mul_f32 v[52:53], v[52:53], v[196:197]
	v_pk_mul_f32 v[2:3], v[130:131], v[2:3] op_sel_hi:[0, 1]
	v_pk_mul_f32 v[52:53], v[130:131], v[52:53] op_sel_hi:[0, 1]
	v_pk_mul_f32 v[48:49], v[48:49], v[196:197]
	v_cvt_pk_bf16_f32 v52, v52, v53
	v_cvt_pk_bf16_f32 v53, v2, v3
	v_pk_mul_f32 v[2:3], v[50:51], v[198:199]
	v_pk_mul_f32 v[48:49], v[128:129], v[48:49] op_sel_hi:[0, 1]
	global_store_dwordx2 v[124:125], v[52:53], off offset:288
	v_pk_mul_f32 v[2:3], v[128:129], v[2:3] op_sel_hi:[0, 1]
	v_cvt_pk_bf16_f32 v48, v48, v49
	v_cvt_pk_bf16_f32 v49, v2, v3
	global_store_dwordx2 v[0:1], v[48:49], off offset:288
	v_pk_mul_f32 v[2:3], v[46:47], v[202:203]
	v_pk_mul_f32 v[44:45], v[44:45], v[200:201]
	v_pk_mul_f32 v[2:3], v[130:131], v[2:3] op_sel_hi:[0, 1]
	v_pk_mul_f32 v[44:45], v[130:131], v[44:45] op_sel_hi:[0, 1]
	v_pk_mul_f32 v[40:41], v[40:41], v[200:201]
	v_cvt_pk_bf16_f32 v44, v44, v45
	v_cvt_pk_bf16_f32 v45, v2, v3
	v_pk_mul_f32 v[2:3], v[42:43], v[202:203]
	v_pk_mul_f32 v[40:41], v[128:129], v[40:41] op_sel_hi:[0, 1]
	global_store_dwordx2 v[124:125], v[44:45], off offset:320
	v_pk_mul_f32 v[2:3], v[128:129], v[2:3] op_sel_hi:[0, 1]
	v_cvt_pk_bf16_f32 v40, v40, v41
	v_cvt_pk_bf16_f32 v41, v2, v3
	global_store_dwordx2 v[0:1], v[40:41], off offset:320
	v_pk_mul_f32 v[2:3], v[38:39], v[150:151]
	v_pk_mul_f32 v[36:37], v[36:37], v[148:149]
	v_pk_mul_f32 v[2:3], v[130:131], v[2:3] op_sel_hi:[0, 1]
	v_pk_mul_f32 v[36:37], v[130:131], v[36:37] op_sel_hi:[0, 1]
	v_pk_mul_f32 v[32:33], v[32:33], v[148:149]
	v_cvt_pk_bf16_f32 v36, v36, v37
	v_cvt_pk_bf16_f32 v37, v2, v3
	v_pk_mul_f32 v[2:3], v[34:35], v[150:151]
	v_pk_mul_f32 v[32:33], v[128:129], v[32:33] op_sel_hi:[0, 1]
	global_store_dwordx2 v[124:125], v[36:37], off offset:352
	v_pk_mul_f32 v[2:3], v[128:129], v[2:3] op_sel_hi:[0, 1]
	v_cvt_pk_bf16_f32 v32, v32, v33
	v_cvt_pk_bf16_f32 v33, v2, v3
	global_store_dwordx2 v[0:1], v[32:33], off offset:352
	v_pk_mul_f32 v[2:3], v[30:31], v[154:155]
	v_pk_mul_f32 v[28:29], v[28:29], v[152:153]
	v_pk_mul_f32 v[2:3], v[130:131], v[2:3] op_sel_hi:[0, 1]
	v_pk_mul_f32 v[28:29], v[130:131], v[28:29] op_sel_hi:[0, 1]
	v_pk_mul_f32 v[24:25], v[24:25], v[152:153]
	v_cvt_pk_bf16_f32 v28, v28, v29
	v_cvt_pk_bf16_f32 v29, v2, v3
	v_pk_mul_f32 v[2:3], v[26:27], v[154:155]
	v_pk_mul_f32 v[24:25], v[128:129], v[24:25] op_sel_hi:[0, 1]
	global_store_dwordx2 v[124:125], v[28:29], off offset:384
	v_pk_mul_f32 v[2:3], v[128:129], v[2:3] op_sel_hi:[0, 1]
	v_cvt_pk_bf16_f32 v24, v24, v25
	v_cvt_pk_bf16_f32 v25, v2, v3
	global_store_dwordx2 v[0:1], v[24:25], off offset:384
	v_pk_mul_f32 v[20:21], v[20:21], v[240:241]
	v_pk_mul_f32 v[2:3], v[22:23], v[242:243]
	v_pk_mul_f32 v[20:21], v[130:131], v[20:21] op_sel_hi:[0, 1]
	v_pk_mul_f32 v[2:3], v[130:131], v[2:3] op_sel_hi:[0, 1]
	v_cvt_pk_bf16_f32 v20, v20, v21
	v_cvt_pk_bf16_f32 v21, v2, v3
	global_store_dwordx2 v[124:125], v[20:21], off offset:416
	v_pk_mul_f32 v[20:21], v[134:135], v[240:241]
	v_pk_mul_f32 v[2:3], v[132:133], v[242:243]
	v_pk_mul_f32 v[20:21], v[128:129], v[20:21] op_sel_hi:[0, 1]
	v_pk_mul_f32 v[2:3], v[128:129], v[2:3] op_sel_hi:[0, 1]
	v_cvt_pk_bf16_f32 v20, v20, v21
	v_cvt_pk_bf16_f32 v21, v2, v3
	global_store_dwordx2 v[0:1], v[20:21], off offset:416
	v_pk_mul_f32 v[2:3], v[12:13], v[246:247]
	v_pk_mul_f32 v[12:13], v[14:15], v[244:245]
	v_pk_mul_f32 v[2:3], v[130:131], v[2:3] op_sel_hi:[0, 1]
	v_pk_mul_f32 v[12:13], v[130:131], v[12:13] op_sel_hi:[0, 1]
	v_pk_mul_f32 v[8:9], v[8:9], v[244:245]
	v_cvt_pk_bf16_f32 v12, v12, v13
	v_cvt_pk_bf16_f32 v13, v2, v3
	v_pk_mul_f32 v[2:3], v[10:11], v[246:247]
	v_pk_mul_f32 v[8:9], v[128:129], v[8:9] op_sel_hi:[0, 1]
	global_store_dwordx2 v[124:125], v[12:13], off offset:448
	v_pk_mul_f32 v[2:3], v[128:129], v[2:3] op_sel_hi:[0, 1]
	v_cvt_pk_bf16_f32 v8, v8, v9
	v_cvt_pk_bf16_f32 v9, v2, v3
	global_store_dwordx2 v[0:1], v[8:9], off offset:448
	v_pk_mul_f32 v[4:5], v[4:5], v[248:249]
	v_pk_mul_f32 v[2:3], v[6:7], v[250:251]
	v_pk_mul_f32 v[4:5], v[130:131], v[4:5] op_sel_hi:[0, 1]
	v_pk_mul_f32 v[2:3], v[130:131], v[2:3] op_sel_hi:[0, 1]
	v_cvt_pk_bf16_f32 v4, v4, v5
	v_cvt_pk_bf16_f32 v5, v2, v3
	global_store_dwordx2 v[124:125], v[4:5], off offset:480
	v_pk_mul_f32 v[4:5], v[18:19], v[248:249]
	v_pk_mul_f32 v[2:3], v[16:17], v[250:251]
	v_pk_mul_f32 v[4:5], v[128:129], v[4:5] op_sel_hi:[0, 1]
	v_pk_mul_f32 v[2:3], v[128:129], v[2:3] op_sel_hi:[0, 1]
	v_cvt_pk_bf16_f32 v4, v4, v5
	v_cvt_pk_bf16_f32 v5, v2, v3
	global_store_dwordx2 v[0:1], v[4:5], off offset:480
	s_branch .LBB0_297
